# code placement: both attention key-loop heads pinned to 64-byte boundaries (p2align 6), later code kept at its offset mod 64
# speedup vs baseline: 1.0097x; 1.0022x over previous
.LBB0_1321:
	s_waitcnt vmcnt(0)
	s_mov_b64 s[34:35], 0
	.p2align	6

.Latt_exitA:
	v_mov_b64_e32 v[6:7], v[184:185]
	v_mov_b64_e32 v[8:9], v[186:187]
	s_branch .LBB0_1333
	s_nop 0
	s_nop 0
	s_nop 0
	s_nop 0
	s_nop 0
	s_nop 0
	s_nop 0
	s_nop 0
	s_nop 0
	s_nop 0
	s_nop 0
	s_nop 0
